# phase 5 epilogue rewritten by hand: x rows two blocks ahead in flight, half-row accumulator exchange so f32 accesses cover 8 rows x 128 B, row sums of squares reduced with one extra half-row add
# baseline (speedup 1.0000x reference)
; #define PG8_STAGE(bufoff, gbase, voff) do { _Pragma("unroll") for (int _i = 0; _i < 2; ++_i) \
;         __builtin_amdgcn_global_load_lds((const unsigned*)((const char*)(gbase) + (voff)[_i]), (PG8_LAS unsigned*)(lds + (bufoff) + ldsw + _i * 8192), 16, 0, 0); } while (0)
; #define PG8_LDA(dst, b, h) do { _Pragma("unroll") for (int m = 0; m < 4; ++m) _Pragma("unroll") for (int k = 0; k < 2; ++k) dst[m][k] = *(const PG8_LAS bf16x8*)(lds + PG8_SA(b, h) + aoff + m * 2048 + k * 1024); } while (0)
; #define PG8_LDB(dst, b, h) do { _Pragma("unroll") for (int n = 0; n < 2; ++n) _Pragma("unroll") for (int k = 0; k < 2; ++k) dst[n][k] = *(const PG8_LAS bf16x8*)(lds + PG8_SB(b, h) + boff + n * 2048 + k * 1024); } while (0)
; #define PG8_MMA(ai, bj, At, Bt) do { __builtin_amdgcn_s_setprio(1); _Pragma("unroll") for (int m = 0; m < 4; ++m) _Pragma("unroll") for (int n = 0; n < 2; ++n) _Pragma("unroll") for (int k = 0; k < 2; ++k) \
;         acc[ai][bj][m][n] = __builtin_amdgcn_mfma_f32_16x16x32_bf16(Bt[n][k], At[m][k], acc[ai][bj][m][n], 0, 0, 0); __builtin_amdgcn_s_setprio(0); } while (0)
; #define PG8_WAIT_L(n) asm volatile("s_waitcnt lgkmcnt(" #n ")" ::: "memory")
; #define PG8_BAR __builtin_amdgcn_s_barrier()
; #define PG8_SCHED __builtin_amdgcn_sched_barrier(0)
; template <class Epi, class Sched>
; __device__ __forceinline__ void gemm_phase(PG8_LAS unsigned char* lds, const Gemm g, const Sched& S, const Epi& E) {
;     ...
;             PG8_LDB(B0, 0, 0); PG8_SCHED; PG8_LDA(At, 0, 0); PG8_STAGE(PG8_SA(1, 1), a1 + hstep, voffA);
;             PG8_WAIT_L(8); PG8_BAR; PG8_WAIT_L(0); PG8_MMA(0, 0, At, B0); PG8_BAR; PG8_SCHED;
;             PG8_LDB(B1, 0, 1); PG8_STAGE(PG8_SB(0, 0), b2, voffB);
;             PG8_BAR; PG8_WAIT_L(0); PG8_MMA(0, 1, At, B1); PG8_BAR;
;             PG8_LDA(At, 0, 1); PG8_STAGE(PG8_SA(0, 0), a2, voffA);
;             PG8_BAR; PG8_WAIT_L(0); PG8_MMA(1, 0, At, B0); PG8_BAR; PG8_SCHED;
;             PG8_STAGE(PG8_SB(0, 1), b2 + hstep, voffB);
.LBB0_750:
	ds_read_b128 v[138:141], v147
	ds_read_b128 v[164:167], v148
	ds_read_b128 v[168:171], v149
	ds_read_b128 v[172:175], v150
	s_add_u32 s30, s28, 0xfffc0080
	s_addc_u32 s31, s29, -1
	s_cmp_eq_u32 s64, 12
	s_cselect_b32 s35, s17, s31
	s_cselect_b32 s34, s25, s30
	s_cselect_b32 s31, s15, s63
	s_cselect_b32 s30, s61, s62
	s_mov_b32 m0, s59
	v_lshl_add_u64 v[142:143], s[28:29], 0, v[134:135]
	ds_read_b128 v[176:179], v145
	ds_read_b128 v[180:183], v145 offset:1024
	ds_read_b128 v[184:187], v145 offset:2048
	ds_read_b128 v[188:191], v145 offset:3072
	ds_read_b128 v[192:195], v145 offset:4096
	ds_read_b128 v[196:199], v145 offset:5120
	ds_read_b128 v[200:203], v145 offset:6144
	ds_read_b128 v[204:207], v145 offset:7168
	global_load_lds_dwordx4 v[142:143], off
	v_lshl_add_u64 v[142:143], s[28:29], 0, v[136:137]
	s_mov_b32 m0, s60
	s_nop 0
	global_load_lds_dwordx4 v[142:143], off
	s_waitcnt lgkmcnt(8)
	s_barrier
	s_waitcnt lgkmcnt(0)
	s_setprio 1
	s_waitcnt lgkmcnt(0)
	v_mfma_f32_16x16x32_bf16 v[126:129], v[138:141], v[176:179], v[126:129]
	v_mfma_f32_16x16x32_bf16 v[122:125], v[168:171], v[176:179], v[122:125]
	v_mfma_f32_16x16x32_bf16 v[110:113], v[138:141], v[184:187], v[110:113]
	v_mfma_f32_16x16x32_bf16 v[106:109], v[168:171], v[184:187], v[106:109]
	v_mfma_f32_16x16x32_bf16 v[94:97], v[138:141], v[192:195], v[94:97]
	v_mfma_f32_16x16x32_bf16 v[90:93], v[168:171], v[192:195], v[90:93]
	v_mfma_f32_16x16x32_bf16 v[78:81], v[138:141], v[200:203], v[78:81]
	v_mfma_f32_16x16x32_bf16 v[74:77], v[168:171], v[200:203], v[74:77]
	v_mfma_f32_16x16x32_bf16 v[126:129], v[164:167], v[180:183], v[126:129]
	v_mfma_f32_16x16x32_bf16 v[122:125], v[172:175], v[180:183], v[122:125]
	v_mfma_f32_16x16x32_bf16 v[110:113], v[164:167], v[188:191], v[110:113]
	v_mfma_f32_16x16x32_bf16 v[106:109], v[172:175], v[188:191], v[106:109]
	v_mfma_f32_16x16x32_bf16 v[94:97], v[164:167], v[196:199], v[94:97]
	v_mfma_f32_16x16x32_bf16 v[90:93], v[172:175], v[196:199], v[90:93]
	v_mfma_f32_16x16x32_bf16 v[78:81], v[164:167], v[204:207], v[78:81]
	v_mfma_f32_16x16x32_bf16 v[74:77], v[172:175], v[204:207], v[74:77]
	s_setprio 0
	s_barrier
	s_mov_b32 m0, s27
	v_lshl_add_u64 v[142:143], s[30:31], 0, v[130:131]
	ds_read_b128 v[208:211], v151
	ds_read_b128 v[212:215], v152
	ds_read_b128 v[216:219], v153
	ds_read_b128 v[220:223], v154
	global_load_lds_dwordx4 v[142:143], off
	v_lshl_add_u64 v[224:225], s[30:31], 0, v[132:133]
	s_mov_b32 m0, s41
	s_nop 0
	global_load_lds_dwordx4 v[224:225], off
	s_barrier
	s_waitcnt lgkmcnt(0)
	s_setprio 1
	s_waitcnt lgkmcnt(0)
	v_mfma_f32_16x16x32_bf16 v[118:121], v[208:211], v[176:179], v[118:121]
	v_mfma_f32_16x16x32_bf16 v[114:117], v[216:219], v[176:179], v[114:117]
	v_mfma_f32_16x16x32_bf16 v[102:105], v[208:211], v[184:187], v[102:105]
	v_mfma_f32_16x16x32_bf16 v[98:101], v[216:219], v[184:187], v[98:101]
	v_mfma_f32_16x16x32_bf16 v[86:89], v[208:211], v[192:195], v[86:89]
	v_mfma_f32_16x16x32_bf16 v[82:85], v[216:219], v[192:195], v[82:85]
	v_mfma_f32_16x16x32_bf16 v[70:73], v[208:211], v[200:203], v[70:73]
	v_mfma_f32_16x16x32_bf16 v[66:69], v[216:219], v[200:203], v[66:69]
	v_mfma_f32_16x16x32_bf16 v[118:121], v[212:215], v[180:183], v[118:121]
	v_mfma_f32_16x16x32_bf16 v[114:117], v[220:223], v[180:183], v[114:117]
	v_mfma_f32_16x16x32_bf16 v[102:105], v[212:215], v[188:191], v[102:105]
	v_mfma_f32_16x16x32_bf16 v[98:101], v[220:223], v[188:191], v[98:101]
	v_mfma_f32_16x16x32_bf16 v[86:89], v[212:215], v[196:199], v[86:89]
	v_mfma_f32_16x16x32_bf16 v[82:85], v[220:223], v[196:199], v[82:85]
	v_mfma_f32_16x16x32_bf16 v[70:73], v[212:215], v[204:207], v[70:73]
	v_mfma_f32_16x16x32_bf16 v[66:69], v[220:223], v[204:207], v[66:69]
	s_setprio 0
	s_mov_b32 m0, s40
	v_lshl_add_u64 v[226:227], s[34:35], 0, v[130:131]
	s_barrier
	ds_read_b128 v[176:179], v145 offset:16384
	ds_read_b128 v[180:183], v145 offset:17408
	ds_read_b128 v[184:187], v145 offset:18432
	ds_read_b128 v[188:191], v145 offset:19456
	ds_read_b128 v[192:195], v145 offset:20480
	ds_read_b128 v[196:199], v145 offset:21504
	ds_read_b128 v[200:203], v145 offset:22528
	ds_read_b128 v[204:207], v145 offset:23552
	global_load_lds_dwordx4 v[226:227], off
	v_lshl_add_u64 v[228:229], s[34:35], 0, v[132:133]
	s_mov_b32 m0, s42
	s_nop 0
	global_load_lds_dwordx4 v[228:229], off
	s_barrier
	s_waitcnt lgkmcnt(0)
	s_setprio 1
	s_waitcnt lgkmcnt(0)
	v_mfma_f32_16x16x32_bf16 v[62:65], v[138:141], v[176:179], v[62:65]
	v_mfma_f32_16x16x32_bf16 v[58:61], v[168:171], v[176:179], v[58:61]
	v_mfma_f32_16x16x32_bf16 v[46:49], v[138:141], v[184:187], v[46:49]
	v_mfma_f32_16x16x32_bf16 v[42:45], v[168:171], v[184:187], v[42:45]
	v_mfma_f32_16x16x32_bf16 v[30:33], v[138:141], v[192:195], v[30:33]
	v_mfma_f32_16x16x32_bf16 v[26:29], v[168:171], v[192:195], v[26:29]
	v_mfma_f32_16x16x32_bf16 v[14:17], v[138:141], v[200:203], v[14:17]
	v_mfma_f32_16x16x32_bf16 v[10:13], v[168:171], v[200:203], v[10:13]
	v_mfma_f32_16x16x32_bf16 v[62:65], v[164:167], v[180:183], v[62:65]
	v_mfma_f32_16x16x32_bf16 v[58:61], v[172:175], v[180:183], v[58:61]
	v_mfma_f32_16x16x32_bf16 v[46:49], v[164:167], v[188:191], v[46:49]
	v_mfma_f32_16x16x32_bf16 v[42:45], v[172:175], v[188:191], v[42:45]
	v_mfma_f32_16x16x32_bf16 v[30:33], v[164:167], v[196:199], v[30:33]
	v_mfma_f32_16x16x32_bf16 v[26:29], v[172:175], v[196:199], v[26:29]
	v_mfma_f32_16x16x32_bf16 v[14:17], v[164:167], v[204:207], v[14:17]
	v_mfma_f32_16x16x32_bf16 v[10:13], v[172:175], v[204:207], v[10:13]
	s_setprio 0
	s_barrier
; #define PG8_STAGE(bufoff, gbase, voff) do { _Pragma("unroll") for (int _i = 0; _i < 2; ++_i) \
;         __builtin_amdgcn_global_load_lds((const unsigned*)((const char*)(gbase) + (voff)[_i]), (PG8_LAS unsigned*)(lds + (bufoff) + ldsw + _i * 8192), 16, 0, 0); } while (0)
; #define PG8_LDA(dst, b, h) do { _Pragma("unroll") for (int m = 0; m < 4; ++m) _Pragma("unroll") for (int k = 0; k < 2; ++k) dst[m][k] = *(const PG8_LAS bf16x8*)(lds + PG8_SA(b, h) + aoff + m * 2048 + k * 1024); } while (0)
; #define PG8_LDB(dst, b, h) do { _Pragma("unroll") for (int n = 0; n < 2; ++n) _Pragma("unroll") for (int k = 0; k < 2; ++k) dst[n][k] = *(const PG8_LAS bf16x8*)(lds + PG8_SB(b, h) + boff + n * 2048 + k * 1024); } while (0)
; #define PG8_MMA(ai, bj, At, Bt) do { __builtin_amdgcn_s_setprio(1); _Pragma("unroll") for (int m = 0; m < 4; ++m) _Pragma("unroll") for (int n = 0; n < 2; ++n) _Pragma("unroll") for (int k = 0; k < 2; ++k) \
;         acc[ai][bj][m][n] = __builtin_amdgcn_mfma_f32_16x16x32_bf16(Bt[n][k], At[m][k], acc[ai][bj][m][n], 0, 0, 0); __builtin_amdgcn_s_setprio(0); } while (0)
; #define PG8_WAIT_V(n) asm volatile("s_waitcnt vmcnt(" #n ")" ::: "memory")
; #define PG8_WAIT_L(n) asm volatile("s_waitcnt lgkmcnt(" #n ")" ::: "memory")
; #define PG8_BAR __builtin_amdgcn_s_barrier()
; #define PG8_SCHED __builtin_amdgcn_sched_barrier(0)
; template <class Epi, class Sched>
; __device__ __forceinline__ void gemm_phase(PG8_LAS unsigned char* lds, const Gemm g, const Sched& S, const Epi& E) {
;     ...
;             PG8_STAGE(PG8_SB(0, 1), b2 + hstep, voffB);
;             PG8_WAIT_V(6); PG8_BAR; PG8_MMA(1, 1, At, B1); PG8_BAR;
;             PG8_LDB(B0, 1, 0); PG8_SCHED; PG8_LDA(At, 1, 0); PG8_STAGE(PG8_SA(0, 1), a2 + hstep, voffA);
;             PG8_WAIT_L(8); PG8_BAR; PG8_WAIT_L(0); PG8_MMA(0, 0, At, B0); PG8_BAR; PG8_SCHED;
;             PG8_LDB(B1, 1, 1); PG8_STAGE(PG8_SB(1, 0), b3, voffB);
;             PG8_BAR; PG8_WAIT_L(0); PG8_MMA(0, 1, At, B1); PG8_BAR;
;             PG8_LDA(At, 1, 1); PG8_STAGE(PG8_SA(1, 0), a3, voffA);
;             PG8_BAR; PG8_WAIT_L(0); PG8_MMA(1, 0, At, B0); PG8_BAR; PG8_SCHED;
	s_add_u32 s66, s30, 0x40000
	s_addc_u32 s67, s31, 0
	s_mov_b32 m0, s43
	v_lshl_add_u64 v[138:139], s[66:67], 0, v[130:131]
	global_load_lds_dwordx4 v[138:139], off
	v_lshl_add_u64 v[138:139], s[66:67], 0, v[132:133]
	s_mov_b32 m0, s44
	s_nop 0
	global_load_lds_dwordx4 v[138:139], off
	s_waitcnt vmcnt(6)
	s_barrier
	s_setprio 1
	v_mfma_f32_16x16x32_bf16 v[54:57], v[208:211], v[176:179], v[54:57]
	v_mfma_f32_16x16x32_bf16 v[50:53], v[216:219], v[176:179], v[50:53]
	v_mfma_f32_16x16x32_bf16 v[38:41], v[208:211], v[184:187], v[38:41]
	v_mfma_f32_16x16x32_bf16 v[34:37], v[216:219], v[184:187], v[34:37]
	v_mfma_f32_16x16x32_bf16 v[22:25], v[208:211], v[192:195], v[22:25]
	v_mfma_f32_16x16x32_bf16 v[18:21], v[216:219], v[192:195], v[18:21]
	v_mfma_f32_16x16x32_bf16 v[6:9], v[208:211], v[200:203], v[6:9]
	v_mfma_f32_16x16x32_bf16 v[2:5], v[216:219], v[200:203], v[2:5]
	v_mfma_f32_16x16x32_bf16 v[54:57], v[212:215], v[180:183], v[54:57]
	v_mfma_f32_16x16x32_bf16 v[50:53], v[220:223], v[180:183], v[50:53]
	v_mfma_f32_16x16x32_bf16 v[38:41], v[212:215], v[188:191], v[38:41]
	v_mfma_f32_16x16x32_bf16 v[34:37], v[220:223], v[188:191], v[34:37]
	v_mfma_f32_16x16x32_bf16 v[22:25], v[212:215], v[196:199], v[22:25]
	v_mfma_f32_16x16x32_bf16 v[18:21], v[220:223], v[196:199], v[18:21]
	v_mfma_f32_16x16x32_bf16 v[6:9], v[212:215], v[204:207], v[6:9]
	v_mfma_f32_16x16x32_bf16 v[2:5], v[220:223], v[204:207], v[2:5]
	s_setprio 0
	s_barrier
	ds_read_b128 v[138:141], v155
	ds_read_b128 v[164:167], v156
	ds_read_b128 v[168:171], v157
	ds_read_b128 v[172:175], v158
	s_add_u32 s34, s34, 0x40000
	s_addc_u32 s35, s35, 0
	s_mov_b32 m0, s45
	v_lshl_add_u64 v[208:209], s[34:35], 0, v[130:131]
	ds_read_b128 v[176:179], v145 offset:32768
	ds_read_b128 v[180:183], v145 offset:33792
	ds_read_b128 v[184:187], v145 offset:34816
	ds_read_b128 v[188:191], v145 offset:35840
	ds_read_b128 v[192:195], v145 offset:36864
	ds_read_b128 v[196:199], v145 offset:37888
	ds_read_b128 v[200:203], v145 offset:38912
	ds_read_b128 v[204:207], v145 offset:39936
	global_load_lds_dwordx4 v[208:209], off
	v_lshl_add_u64 v[208:209], s[34:35], 0, v[132:133]
	s_mov_b32 m0, s46
	s_nop 0
	global_load_lds_dwordx4 v[208:209], off
	s_waitcnt lgkmcnt(8)
	s_barrier
	s_waitcnt lgkmcnt(0)
	s_setprio 1
	s_waitcnt lgkmcnt(0)
	v_mfma_f32_16x16x32_bf16 v[126:129], v[138:141], v[176:179], v[126:129]
	v_mfma_f32_16x16x32_bf16 v[122:125], v[168:171], v[176:179], v[122:125]
	v_mfma_f32_16x16x32_bf16 v[110:113], v[138:141], v[184:187], v[110:113]
	v_mfma_f32_16x16x32_bf16 v[106:109], v[168:171], v[184:187], v[106:109]
	v_mfma_f32_16x16x32_bf16 v[94:97], v[138:141], v[192:195], v[94:97]
	v_mfma_f32_16x16x32_bf16 v[90:93], v[168:171], v[192:195], v[90:93]
	v_mfma_f32_16x16x32_bf16 v[78:81], v[138:141], v[200:203], v[78:81]
	v_mfma_f32_16x16x32_bf16 v[74:77], v[168:171], v[200:203], v[74:77]
	v_mfma_f32_16x16x32_bf16 v[126:129], v[164:167], v[180:183], v[126:129]
	v_mfma_f32_16x16x32_bf16 v[122:125], v[172:175], v[180:183], v[122:125]
	v_mfma_f32_16x16x32_bf16 v[110:113], v[164:167], v[188:191], v[110:113]
	v_mfma_f32_16x16x32_bf16 v[106:109], v[172:175], v[188:191], v[106:109]
	v_mfma_f32_16x16x32_bf16 v[94:97], v[164:167], v[196:199], v[94:97]
	v_mfma_f32_16x16x32_bf16 v[90:93], v[172:175], v[196:199], v[90:93]
	v_mfma_f32_16x16x32_bf16 v[78:81], v[164:167], v[204:207], v[78:81]
	v_mfma_f32_16x16x32_bf16 v[74:77], v[172:175], v[204:207], v[74:77]
	s_setprio 0
	s_barrier
	s_mov_b32 m0, s47
	v_lshl_add_u64 v[142:143], v[142:143], 0, s[8:9]
	ds_read_b128 v[208:211], v159
	ds_read_b128 v[212:215], v160
	ds_read_b128 v[216:219], v161
	ds_read_b128 v[220:223], v162
	global_load_lds_dwordx4 v[142:143], off
	v_lshl_add_u64 v[142:143], v[224:225], 0, s[8:9]
	s_mov_b32 m0, s48
	s_nop 0
	global_load_lds_dwordx4 v[142:143], off
	s_barrier
	s_waitcnt lgkmcnt(0)
	s_setprio 1
	s_waitcnt lgkmcnt(0)
	v_mfma_f32_16x16x32_bf16 v[118:121], v[208:211], v[176:179], v[118:121]
	v_mfma_f32_16x16x32_bf16 v[114:117], v[216:219], v[176:179], v[114:117]
	v_mfma_f32_16x16x32_bf16 v[102:105], v[208:211], v[184:187], v[102:105]
	v_mfma_f32_16x16x32_bf16 v[98:101], v[216:219], v[184:187], v[98:101]
	v_mfma_f32_16x16x32_bf16 v[86:89], v[208:211], v[192:195], v[86:89]
	v_mfma_f32_16x16x32_bf16 v[82:85], v[216:219], v[192:195], v[82:85]
	v_mfma_f32_16x16x32_bf16 v[70:73], v[208:211], v[200:203], v[70:73]
	v_mfma_f32_16x16x32_bf16 v[66:69], v[216:219], v[200:203], v[66:69]
	v_mfma_f32_16x16x32_bf16 v[118:121], v[212:215], v[180:183], v[118:121]
	v_mfma_f32_16x16x32_bf16 v[114:117], v[220:223], v[180:183], v[114:117]
	v_mfma_f32_16x16x32_bf16 v[102:105], v[212:215], v[188:191], v[102:105]
	v_mfma_f32_16x16x32_bf16 v[98:101], v[220:223], v[188:191], v[98:101]
	v_mfma_f32_16x16x32_bf16 v[86:89], v[212:215], v[196:199], v[86:89]
	v_mfma_f32_16x16x32_bf16 v[82:85], v[220:223], v[196:199], v[82:85]
	v_mfma_f32_16x16x32_bf16 v[70:73], v[212:215], v[204:207], v[70:73]
	v_mfma_f32_16x16x32_bf16 v[66:69], v[220:223], v[204:207], v[66:69]
	s_setprio 0
	s_mov_b32 m0, s49
	v_lshl_add_u64 v[142:143], v[226:227], 0, s[8:9]
	s_barrier
	ds_read_b128 v[176:179], v145 offset:49152
	ds_read_b128 v[180:183], v145 offset:50176
	ds_read_b128 v[184:187], v145 offset:51200
	ds_read_b128 v[188:191], v145 offset:52224
	ds_read_b128 v[192:195], v145 offset:53248
	ds_read_b128 v[196:199], v145 offset:54272
	ds_read_b128 v[200:203], v145 offset:55296
	ds_read_b128 v[204:207], v145 offset:56320
	global_load_lds_dwordx4 v[142:143], off
	v_lshl_add_u64 v[142:143], v[228:229], 0, s[8:9]
	s_mov_b32 m0, s50
	s_nop 0
	global_load_lds_dwordx4 v[142:143], off
	s_barrier
; #define PG8_STAGE(bufoff, gbase, voff) do { _Pragma("unroll") for (int _i = 0; _i < 2; ++_i) \
;         __builtin_amdgcn_global_load_lds((const unsigned*)((const char*)(gbase) + (voff)[_i]), (PG8_LAS unsigned*)(lds + (bufoff) + ldsw + _i * 8192), 16, 0, 0); } while (0)
; #define PG8_MMA(ai, bj, At, Bt) do { __builtin_amdgcn_s_setprio(1); _Pragma("unroll") for (int m = 0; m < 4; ++m) _Pragma("unroll") for (int n = 0; n < 2; ++n) _Pragma("unroll") for (int k = 0; k < 2; ++k) \
;         acc[ai][bj][m][n] = __builtin_amdgcn_mfma_f32_16x16x32_bf16(Bt[n][k], At[m][k], acc[ai][bj][m][n], 0, 0, 0); __builtin_amdgcn_s_setprio(0); } while (0)
; #define PG8_WAIT_V(n) asm volatile("s_waitcnt vmcnt(" #n ")" ::: "memory")
; #define PG8_WAIT_L(n) asm volatile("s_waitcnt lgkmcnt(" #n ")" ::: "memory")
; #define PG8_BAR __builtin_amdgcn_s_barrier()
; #define PG8_SCHED __builtin_amdgcn_sched_barrier(0)
; template <class Epi, class Sched>
; __device__ __forceinline__ void gemm_phase(PG8_LAS unsigned char* lds, const Gemm g, const Sched& S, const Epi& E) {
;     ...
;             PG8_BAR; PG8_WAIT_L(0); PG8_MMA(1, 0, At, B0); PG8_BAR; PG8_SCHED;
;             PG8_STAGE(PG8_SB(1, 1), b3 + hstep, voffB);
;             PG8_WAIT_V(6); PG8_BAR; PG8_MMA(1, 1, At, B1); PG8_BAR;
;   __device__ __forceinline__ void operator()(const acc8_t& acc, const pg8::Unit& u, int wr, int wc, int fr, int fq) const {
;     ...
;       for (int m = 0; m < 4; m++) {
;         const int token = (int)EPI_TOKEN(u, ai, m);
;         const float* xr = xrow(p, token);
;         float ss = 0.f;
; #pragma unroll
;         for (int bj = 0; bj < 2; bj++)
; #pragma unroll
;           for (int n = 0; n < 2; n++) {
;             const int f = EPI_COL(u, bj, n);
;             const float4 xv = *(const float4*)(xr + f);
;             const float4 o = make_float4(xv.x + acc[ai][bj][m][n][0], xv.y + acc[ai][bj][m][n][1], xv.z + acc[ai][bj][m][n][2], xv.w + acc[ai][bj][m][n][3]);
	s_waitcnt lgkmcnt(0)
	s_setprio 1
	s_waitcnt lgkmcnt(0)
	v_mfma_f32_16x16x32_bf16 v[62:65], v[138:141], v[176:179], v[62:65]
	v_mfma_f32_16x16x32_bf16 v[58:61], v[168:171], v[176:179], v[58:61]
	v_mfma_f32_16x16x32_bf16 v[46:49], v[138:141], v[184:187], v[46:49]
	v_mfma_f32_16x16x32_bf16 v[42:45], v[168:171], v[184:187], v[42:45]
	v_mfma_f32_16x16x32_bf16 v[30:33], v[138:141], v[192:195], v[30:33]
	v_mfma_f32_16x16x32_bf16 v[26:29], v[168:171], v[192:195], v[26:29]
	v_mfma_f32_16x16x32_bf16 v[14:17], v[138:141], v[200:203], v[14:17]
	v_mfma_f32_16x16x32_bf16 v[10:13], v[168:171], v[200:203], v[10:13]
	v_mfma_f32_16x16x32_bf16 v[62:65], v[164:167], v[180:183], v[62:65]
	v_mfma_f32_16x16x32_bf16 v[58:61], v[172:175], v[180:183], v[58:61]
	v_mfma_f32_16x16x32_bf16 v[46:49], v[164:167], v[188:191], v[46:49]
	v_mfma_f32_16x16x32_bf16 v[42:45], v[172:175], v[188:191], v[42:45]
	v_mfma_f32_16x16x32_bf16 v[30:33], v[164:167], v[196:199], v[30:33]
	v_mfma_f32_16x16x32_bf16 v[26:29], v[172:175], v[196:199], v[26:29]
	v_mfma_f32_16x16x32_bf16 v[14:17], v[164:167], v[204:207], v[14:17]
	v_mfma_f32_16x16x32_bf16 v[10:13], v[172:175], v[204:207], v[10:13]
	s_setprio 0
	s_barrier
	s_add_u32 s30, s30, 0x40080
	s_addc_u32 s31, s31, 0
	s_mov_b32 m0, s51
	v_lshl_add_u64 v[138:139], s[30:31], 0, v[130:131]
	global_load_lds_dwordx4 v[138:139], off
	v_lshl_add_u64 v[138:139], s[30:31], 0, v[132:133]
	s_mov_b32 m0, s56
	s_nop 0
	global_load_lds_dwordx4 v[138:139], off
	s_waitcnt vmcnt(6)
	s_barrier
	s_setprio 1
	v_mfma_f32_16x16x32_bf16 v[54:57], v[208:211], v[176:179], v[54:57]
	v_mfma_f32_16x16x32_bf16 v[50:53], v[216:219], v[176:179], v[50:53]
	v_mfma_f32_16x16x32_bf16 v[38:41], v[208:211], v[184:187], v[38:41]
	v_mfma_f32_16x16x32_bf16 v[34:37], v[216:219], v[184:187], v[34:37]
	v_mfma_f32_16x16x32_bf16 v[22:25], v[208:211], v[192:195], v[22:25]
	v_mfma_f32_16x16x32_bf16 v[18:21], v[216:219], v[192:195], v[18:21]
	v_mfma_f32_16x16x32_bf16 v[6:9], v[208:211], v[200:203], v[6:9]
	v_mfma_f32_16x16x32_bf16 v[2:5], v[216:219], v[200:203], v[2:5]
	v_mfma_f32_16x16x32_bf16 v[54:57], v[212:215], v[180:183], v[54:57]
	v_mfma_f32_16x16x32_bf16 v[50:53], v[220:223], v[180:183], v[50:53]
	v_mfma_f32_16x16x32_bf16 v[38:41], v[212:215], v[188:191], v[38:41]
	v_mfma_f32_16x16x32_bf16 v[34:37], v[220:223], v[188:191], v[34:37]
	v_mfma_f32_16x16x32_bf16 v[22:25], v[212:215], v[196:199], v[22:25]
	v_mfma_f32_16x16x32_bf16 v[18:21], v[220:223], v[196:199], v[18:21]
	v_mfma_f32_16x16x32_bf16 v[6:9], v[212:215], v[204:207], v[6:9]
	v_mfma_f32_16x16x32_bf16 v[2:5], v[220:223], v[204:207], v[2:5]
	s_setprio 0
	s_add_i32 s64, s64, 2
	s_add_u32 s28, s28, 0x100
	s_addc_u32 s29, s29, 0
	s_add_u32 s62, s62, 0x100
	s_addc_u32 s63, s63, 0
	s_cmp_gt_u32 s64, 13
	s_barrier
	s_cbranch_scc0 .LBB0_750
	v_readlane_b32 s64, v239, 0
	v_readlane_b32 s65, v239, 1
	v_readlane_b32 s66, v239, 2
	v_readlane_b32 s67, v239, 3
	v_readlane_b32 s68, v239, 4
	v_readlane_b32 s69, v239, 5
	v_readlane_b32 s70, v239, 6
	v_readlane_b32 s71, v239, 7
	v_readlane_b32 s72, v239, 8
	v_readlane_b32 s73, v239, 9
	v_readlane_b32 s74, v239, 10
	v_readlane_b32 s75, v239, 11
	v_readlane_b32 s76, v239, 12
	v_readlane_b32 s77, v239, 13
	v_readlane_b32 s78, v239, 14
	v_readlane_b32 s79, v239, 15
	s_mov_b64 s[52:53], s[64:65]
	s_mov_b64 s[54:55], s[66:67]
	s_cmp_lt_u32 s26, 0x80
	s_cselect_b32 s80, s64, s66
	s_cselect_b32 s81, s65, s67
	s_cselect_b32 s82, 0, 0xffff8000
	v_lshl_or_b32 v164, s24, 8, v146
	v_bfe_u32 v165, v144, 3, 1
	v_and_b32_e32 v166, -9, v144
	v_lshl_add_u32 v167, s26, 8, v144
	v_lshl_add_u32 v166, s26, 8, v166
	v_lshl_add_u32 v164, v165, 4, v164
	v_lshlrev_b32_e32 v163, 2, v167
	v_add_u32_e32 v168, s82, v166
	v_ashrrev_i32_e32 v165, 31, v164
	v_ashrrev_i32_e32 v167, 31, v166
	v_ashrrev_i32_e32 v169, 31, v168
	v_lshlrev_b64 v[170:171], 2, v[164:165]
	v_lshlrev_b64 v[172:173], 1, v[164:165]
	v_lshlrev_b64 v[174:175], 12, v[168:169]
	v_lshlrev_b64 v[176:177], 12, v[166:167]
	v_lshlrev_b64 v[178:179], 11, v[166:167]
	v_lshl_add_u64 v[174:175], s[80:81], 0, v[174:175]
	v_lshl_add_u64 v[176:177], s[86:87], 0, v[176:177]
	v_lshl_add_u64 v[178:179], s[10:11], 0, v[178:179]
	v_lshl_add_u64 v[138:139], v[174:175], 0, v[170:171]
	v_lshl_add_u64 v[142:143], v[176:177], 0, v[170:171]
	v_lshl_add_u64 v[234:235], v[178:179], 0, v[172:173]
	s_mov_b64 s[96:97], 0x8000
	v_lshl_add_u64 v[140:141], v[138:139], 0, s[96:97]
	v_lshl_add_u64 v[232:233], v[142:143], 0, s[96:97]
	s_mov_b64 s[96:97], 0x4000
	v_lshl_add_u64 v[236:237], v[234:235], 0, s[96:97]
	s_mov_b32 s84, 0xff00ff00
	s_mov_b32 s85, 0xff00ff00
	global_load_dwordx4 v[164:167], v[138:139], off
	global_load_dwordx4 v[168:171], v[138:139], off offset:512
	global_load_dwordx4 v[172:175], v[140:141], off
	global_load_dwordx4 v[176:179], v[140:141], off offset:512
	s_mov_b64 s[96:97], 0x10000
	v_lshl_add_u64 v[138:139], v[138:139], 0, s[96:97]
	v_lshl_add_u64 v[140:141], v[140:141], 0, s[96:97]
	global_load_dwordx4 v[180:183], v[138:139], off
	global_load_dwordx4 v[184:187], v[138:139], off offset:512
	global_load_dwordx4 v[188:191], v[140:141], off
	global_load_dwordx4 v[192:195], v[140:141], off offset:512
	v_mov_b32_dpp v228, v122 row_ror:8 row_mask:0xf bank_mask:0xf
	v_mov_b32_dpp v229, v123 row_ror:8 row_mask:0xf bank_mask:0xf
	v_mov_b32_dpp v230, v124 row_ror:8 row_mask:0xf bank_mask:0xf
	v_mov_b32_dpp v231, v125 row_ror:8 row_mask:0xf bank_mask:0xf
	v_mov_b32_dpp v212, v126 row_ror:8 row_mask:0xf bank_mask:0xf
	v_mov_b32_dpp v213, v127 row_ror:8 row_mask:0xf bank_mask:0xf
	v_mov_b32_dpp v214, v128 row_ror:8 row_mask:0xf bank_mask:0xf
;   __device__ __forceinline__ void operator()(const acc8_t& acc, const pg8::Unit& u, int wr, int wc, int fr, int fq) const {
;     ...
;       for (int m = 0; m < 4; m++) {
;         const int token = (int)EPI_TOKEN(u, ai, m);
;         const float* xr = xrow(p, token);
;         float ss = 0.f;
; #pragma unroll
;         for (int bj = 0; bj < 2; bj++)
; #pragma unroll
;           for (int n = 0; n < 2; n++) {
;             const int f = EPI_COL(u, bj, n);
;             const float4 xv = *(const float4*)(xr + f);
;             const float4 o = make_float4(xv.x + acc[ai][bj][m][n][0], xv.y + acc[ai][bj][m][n][1], xv.z + acc[ai][bj][m][n][2], xv.w + acc[ai][bj][m][n][3]);
;             ss += o.x * o.x + o.y * o.y + o.z * o.z + o.w * o.w;
;             *(float4*)(p.out + O_Y + (size_t)token * 1024 + f) = o;
;             uint2 ob; ob.x = pack2(o.x, o.y); ob.y = pack2(o.z, o.w);
;             *(uint2*)(X1B + (size_t)token * 1024 + f) = ob;
;           }
;         ss = xsum16(ss);
;         ss = xsum32(ss);
;         if (fq == 0) atomicAdd(rss + token, ss);
	v_mov_b32_dpp v215, v129 row_ror:8 row_mask:0xf bank_mask:0xf
	v_cndmask_b32_e64 v126, v126, v228, s[84:85]
	v_cndmask_b32_e64 v127, v127, v229, s[84:85]
	v_cndmask_b32_e64 v128, v128, v230, s[84:85]
	v_cndmask_b32_e64 v129, v129, v231, s[84:85]
	v_cndmask_b32_e64 v122, v212, v122, s[84:85]
	v_cndmask_b32_e64 v123, v213, v123, s[84:85]
	v_cndmask_b32_e64 v124, v214, v124, s[84:85]
	v_cndmask_b32_e64 v125, v215, v125, s[84:85]
	v_mov_b32_dpp v228, v114 row_ror:8 row_mask:0xf bank_mask:0xf
	v_mov_b32_dpp v229, v115 row_ror:8 row_mask:0xf bank_mask:0xf
	v_mov_b32_dpp v230, v116 row_ror:8 row_mask:0xf bank_mask:0xf
	v_mov_b32_dpp v231, v117 row_ror:8 row_mask:0xf bank_mask:0xf
	v_mov_b32_dpp v212, v118 row_ror:8 row_mask:0xf bank_mask:0xf
	v_mov_b32_dpp v213, v119 row_ror:8 row_mask:0xf bank_mask:0xf
	v_mov_b32_dpp v214, v120 row_ror:8 row_mask:0xf bank_mask:0xf
	v_mov_b32_dpp v215, v121 row_ror:8 row_mask:0xf bank_mask:0xf
	v_cndmask_b32_e64 v118, v118, v228, s[84:85]
	v_cndmask_b32_e64 v119, v119, v229, s[84:85]
	v_cndmask_b32_e64 v120, v120, v230, s[84:85]
	v_cndmask_b32_e64 v121, v121, v231, s[84:85]
	v_cndmask_b32_e64 v114, v212, v114, s[84:85]
	v_cndmask_b32_e64 v115, v213, v115, s[84:85]
	v_cndmask_b32_e64 v116, v214, v116, s[84:85]
	v_cndmask_b32_e64 v117, v215, v117, s[84:85]
	s_mov_b64 s[96:97], 0x10000
	v_lshl_add_u64 v[138:139], v[138:139], 0, s[96:97]
	v_lshl_add_u64 v[140:141], v[140:141], 0, s[96:97]
	global_load_dwordx4 v[196:199], v[138:139], off
	global_load_dwordx4 v[200:203], v[138:139], off offset:512
	global_load_dwordx4 v[204:207], v[140:141], off
	global_load_dwordx4 v[208:211], v[140:141], off offset:512
	s_waitcnt vmcnt(8)
	v_pk_add_f32 v[164:165], v[164:165], v[126:127]
	v_pk_add_f32 v[166:167], v[166:167], v[128:129]
	v_pk_add_f32 v[172:173], v[172:173], v[122:123]
	v_pk_add_f32 v[174:175], v[174:175], v[124:125]
	v_pk_add_f32 v[168:169], v[168:169], v[118:119]
	v_pk_add_f32 v[170:171], v[170:171], v[120:121]
	v_pk_add_f32 v[176:177], v[176:177], v[114:115]
	v_pk_add_f32 v[178:179], v[178:179], v[116:117]
	global_store_dwordx4 v[142:143], v[164:167], off
	global_store_dwordx4 v[232:233], v[172:175], off
	v_cvt_pk_bf16_f32 v224, v164, v165
	v_cvt_pk_bf16_f32 v225, v166, v167
	v_cvt_pk_bf16_f32 v226, v172, v173
	v_cvt_pk_bf16_f32 v227, v174, v175
	global_store_dwordx2 v[234:235], v[224:225], off
	global_store_dwordx2 v[236:237], v[226:227], off
	global_store_dwordx4 v[142:143], v[168:171], off offset:512
	global_store_dwordx4 v[232:233], v[176:179], off offset:512
	v_cvt_pk_bf16_f32 v220, v168, v169
	v_cvt_pk_bf16_f32 v221, v170, v171
	v_cvt_pk_bf16_f32 v222, v176, v177
	v_cvt_pk_bf16_f32 v223, v178, v179
	global_store_dwordx2 v[234:235], v[220:221], off offset:256
	global_store_dwordx2 v[236:237], v[222:223], off offset:256
	v_mul_f32_e32 v218, v164, v164
	v_mul_f32_e32 v219, v172, v172
	v_fmac_f32_e32 v218, v165, v165
	v_fmac_f32_e32 v219, v173, v173
	v_fmac_f32_e32 v218, v166, v166
	v_fmac_f32_e32 v219, v174, v174
	v_fmac_f32_e32 v218, v167, v167
	v_fmac_f32_e32 v219, v175, v175
	v_fmac_f32_e32 v218, v168, v168
	v_fmac_f32_e32 v219, v176, v176
	v_fmac_f32_e32 v218, v169, v169
	v_fmac_f32_e32 v219, v177, v177
	v_fmac_f32_e32 v218, v170, v170
	v_fmac_f32_e32 v219, v178, v178
	v_fmac_f32_e32 v218, v171, v171
	v_fmac_f32_e32 v219, v179, v179
	v_mov_b32_e32 v216, v218
	v_mov_b32_e32 v217, v219
	s_nop 1
	v_permlane16_swap_b32_e32 v218, v216
	v_permlane16_swap_b32_e32 v219, v217
	v_add_f32_e32 v218, v218, v216
	v_add_f32_e32 v219, v219, v217
	v_mov_b32_e32 v216, v218
	v_mov_b32_e32 v217, v219
	s_nop 1
	v_permlane32_swap_b32_e32 v218, v216
	v_permlane32_swap_b32_e32 v219, v217
	v_add_f32_e32 v218, v218, v216
	v_add_f32_e32 v219, v219, v217
	s_nop 1
	v_add_f32_dpp v216, v218, v218 row_ror:8 row_mask:0xf bank_mask:0xf
	v_add_f32_dpp v217, v219, v219 row_ror:8 row_mask:0xf bank_mask:0xf
	v_cndmask_b32_e64 v216, v216, v217, s[84:85]
	s_and_saveexec_b64 s[82:83], s[4:5]
	global_atomic_add_f32 v163, v216, s[12:13]
	s_or_b64 exec, exec, s[82:83]
	s_mov_b64 s[96:97], 0x10000
	v_lshl_add_u64 v[142:143], v[142:143], 0, s[96:97]
	v_lshl_add_u64 v[232:233], v[232:233], 0, s[96:97]
	s_mov_b64 s[96:97], 0x8000
	v_lshl_add_u64 v[234:235], v[234:235], 0, s[96:97]
	v_lshl_add_u64 v[236:237], v[236:237], 0, s[96:97]
	v_add_u32_e32 v163, 0x40, v163
	v_mov_b32_dpp v228, v106 row_ror:8 row_mask:0xf bank_mask:0xf
	v_mov_b32_dpp v229, v107 row_ror:8 row_mask:0xf bank_mask:0xf
	v_mov_b32_dpp v230, v108 row_ror:8 row_mask:0xf bank_mask:0xf
	v_mov_b32_dpp v231, v109 row_ror:8 row_mask:0xf bank_mask:0xf
	v_mov_b32_dpp v212, v110 row_ror:8 row_mask:0xf bank_mask:0xf
	v_mov_b32_dpp v213, v111 row_ror:8 row_mask:0xf bank_mask:0xf
	v_mov_b32_dpp v214, v112 row_ror:8 row_mask:0xf bank_mask:0xf
	v_mov_b32_dpp v215, v113 row_ror:8 row_mask:0xf bank_mask:0xf
	v_cndmask_b32_e64 v110, v110, v228, s[84:85]
	v_cndmask_b32_e64 v111, v111, v229, s[84:85]
	v_cndmask_b32_e64 v112, v112, v230, s[84:85]
	v_cndmask_b32_e64 v113, v113, v231, s[84:85]
	v_cndmask_b32_e64 v106, v212, v106, s[84:85]
	v_cndmask_b32_e64 v107, v213, v107, s[84:85]
	v_cndmask_b32_e64 v108, v214, v108, s[84:85]
	v_cndmask_b32_e64 v109, v215, v109, s[84:85]
	v_mov_b32_dpp v228, v98 row_ror:8 row_mask:0xf bank_mask:0xf
	v_mov_b32_dpp v229, v99 row_ror:8 row_mask:0xf bank_mask:0xf
	v_mov_b32_dpp v230, v100 row_ror:8 row_mask:0xf bank_mask:0xf
	v_mov_b32_dpp v231, v101 row_ror:8 row_mask:0xf bank_mask:0xf
	v_mov_b32_dpp v212, v102 row_ror:8 row_mask:0xf bank_mask:0xf
	v_mov_b32_dpp v213, v103 row_ror:8 row_mask:0xf bank_mask:0xf
	v_mov_b32_dpp v214, v104 row_ror:8 row_mask:0xf bank_mask:0xf
	v_mov_b32_dpp v215, v105 row_ror:8 row_mask:0xf bank_mask:0xf
	v_cndmask_b32_e64 v102, v102, v228, s[84:85]
	v_cndmask_b32_e64 v103, v103, v229, s[84:85]
	v_cndmask_b32_e64 v104, v104, v230, s[84:85]
	v_cndmask_b32_e64 v105, v105, v231, s[84:85]
	v_cndmask_b32_e64 v98, v212, v98, s[84:85]
	v_cndmask_b32_e64 v99, v213, v99, s[84:85]
	v_cndmask_b32_e64 v100, v214, v100, s[84:85]
	v_cndmask_b32_e64 v101, v215, v101, s[84:85]
	s_mov_b64 s[96:97], 0x10000
	v_lshl_add_u64 v[138:139], v[138:139], 0, s[96:97]
	v_lshl_add_u64 v[140:141], v[140:141], 0, s[96:97]
	global_load_dwordx4 v[164:167], v[138:139], off
	global_load_dwordx4 v[168:171], v[138:139], off offset:512
	global_load_dwordx4 v[172:175], v[140:141], off
	global_load_dwordx4 v[176:179], v[140:141], off offset:512
	s_waitcnt vmcnt(17)
;   __device__ __forceinline__ void operator()(const acc8_t& acc, const pg8::Unit& u, int wr, int wc, int fr, int fq) const {
;     ...
;       for (int m = 0; m < 4; m++) {
;         const int token = (int)EPI_TOKEN(u, ai, m);
;         const float* xr = xrow(p, token);
;         float ss = 0.f;
; #pragma unroll
;         for (int bj = 0; bj < 2; bj++)
; #pragma unroll
;           for (int n = 0; n < 2; n++) {
;             const int f = EPI_COL(u, bj, n);
;             const float4 xv = *(const float4*)(xr + f);
;             const float4 o = make_float4(xv.x + acc[ai][bj][m][n][0], xv.y + acc[ai][bj][m][n][1], xv.z + acc[ai][bj][m][n][2], xv.w + acc[ai][bj][m][n][3]);
;             ss += o.x * o.x + o.y * o.y + o.z * o.z + o.w * o.w;
;             *(float4*)(p.out + O_Y + (size_t)token * 1024 + f) = o;
;             uint2 ob; ob.x = pack2(o.x, o.y); ob.y = pack2(o.z, o.w);
;             *(uint2*)(X1B + (size_t)token * 1024 + f) = ob;
;           }
;         ss = xsum16(ss);
;         ss = xsum32(ss);
;         if (fq == 0) atomicAdd(rss + token, ss);
	v_pk_add_f32 v[180:181], v[180:181], v[110:111]
	v_pk_add_f32 v[182:183], v[182:183], v[112:113]
	v_pk_add_f32 v[188:189], v[188:189], v[106:107]
	v_pk_add_f32 v[190:191], v[190:191], v[108:109]
	v_pk_add_f32 v[184:185], v[184:185], v[102:103]
	v_pk_add_f32 v[186:187], v[186:187], v[104:105]
	v_pk_add_f32 v[192:193], v[192:193], v[98:99]
	v_pk_add_f32 v[194:195], v[194:195], v[100:101]
	global_store_dwordx4 v[142:143], v[180:183], off
	global_store_dwordx4 v[232:233], v[188:191], off
	v_cvt_pk_bf16_f32 v224, v180, v181
	v_cvt_pk_bf16_f32 v225, v182, v183
	v_cvt_pk_bf16_f32 v226, v188, v189
	v_cvt_pk_bf16_f32 v227, v190, v191
	global_store_dwordx2 v[234:235], v[224:225], off
	global_store_dwordx2 v[236:237], v[226:227], off
	global_store_dwordx4 v[142:143], v[184:187], off offset:512
	global_store_dwordx4 v[232:233], v[192:195], off offset:512
	v_cvt_pk_bf16_f32 v220, v184, v185
	v_cvt_pk_bf16_f32 v221, v186, v187
	v_cvt_pk_bf16_f32 v222, v192, v193
	v_cvt_pk_bf16_f32 v223, v194, v195
	global_store_dwordx2 v[234:235], v[220:221], off offset:256
	global_store_dwordx2 v[236:237], v[222:223], off offset:256
	v_mul_f32_e32 v218, v180, v180
	v_mul_f32_e32 v219, v188, v188
	v_fmac_f32_e32 v218, v181, v181
	v_fmac_f32_e32 v219, v189, v189
	v_fmac_f32_e32 v218, v182, v182
	v_fmac_f32_e32 v219, v190, v190
	v_fmac_f32_e32 v218, v183, v183
	v_fmac_f32_e32 v219, v191, v191
	v_fmac_f32_e32 v218, v184, v184
	v_fmac_f32_e32 v219, v192, v192
	v_fmac_f32_e32 v218, v185, v185
	v_fmac_f32_e32 v219, v193, v193
	v_fmac_f32_e32 v218, v186, v186
	v_fmac_f32_e32 v219, v194, v194
	v_fmac_f32_e32 v218, v187, v187
	v_fmac_f32_e32 v219, v195, v195
	v_mov_b32_e32 v216, v218
	v_mov_b32_e32 v217, v219
	s_nop 1
	v_permlane16_swap_b32_e32 v218, v216
	v_permlane16_swap_b32_e32 v219, v217
	v_add_f32_e32 v218, v218, v216
	v_add_f32_e32 v219, v219, v217
	v_mov_b32_e32 v216, v218
	v_mov_b32_e32 v217, v219
	s_nop 1
	v_permlane32_swap_b32_e32 v218, v216
	v_permlane32_swap_b32_e32 v219, v217
	v_add_f32_e32 v218, v218, v216
	v_add_f32_e32 v219, v219, v217
	s_nop 1
	v_add_f32_dpp v216, v218, v218 row_ror:8 row_mask:0xf bank_mask:0xf
	v_add_f32_dpp v217, v219, v219 row_ror:8 row_mask:0xf bank_mask:0xf
	v_cndmask_b32_e64 v216, v216, v217, s[84:85]
	s_and_saveexec_b64 s[82:83], s[4:5]
	global_atomic_add_f32 v163, v216, s[12:13]
	s_or_b64 exec, exec, s[82:83]
	s_mov_b64 s[96:97], 0x10000
	v_lshl_add_u64 v[142:143], v[142:143], 0, s[96:97]
	v_lshl_add_u64 v[232:233], v[232:233], 0, s[96:97]
	s_mov_b64 s[96:97], 0x8000
	v_lshl_add_u64 v[234:235], v[234:235], 0, s[96:97]
	v_lshl_add_u64 v[236:237], v[236:237], 0, s[96:97]
	v_add_u32_e32 v163, 0x40, v163
	v_mov_b32_dpp v228, v90 row_ror:8 row_mask:0xf bank_mask:0xf
	v_mov_b32_dpp v229, v91 row_ror:8 row_mask:0xf bank_mask:0xf
	v_mov_b32_dpp v230, v92 row_ror:8 row_mask:0xf bank_mask:0xf
	v_mov_b32_dpp v231, v93 row_ror:8 row_mask:0xf bank_mask:0xf
	v_mov_b32_dpp v212, v94 row_ror:8 row_mask:0xf bank_mask:0xf
	v_mov_b32_dpp v213, v95 row_ror:8 row_mask:0xf bank_mask:0xf
	v_mov_b32_dpp v214, v96 row_ror:8 row_mask:0xf bank_mask:0xf
	v_mov_b32_dpp v215, v97 row_ror:8 row_mask:0xf bank_mask:0xf
	v_cndmask_b32_e64 v94, v94, v228, s[84:85]
	v_cndmask_b32_e64 v95, v95, v229, s[84:85]
	v_cndmask_b32_e64 v96, v96, v230, s[84:85]
	v_cndmask_b32_e64 v97, v97, v231, s[84:85]
	v_cndmask_b32_e64 v90, v212, v90, s[84:85]
	v_cndmask_b32_e64 v91, v213, v91, s[84:85]
	v_cndmask_b32_e64 v92, v214, v92, s[84:85]
	v_cndmask_b32_e64 v93, v215, v93, s[84:85]
	v_mov_b32_dpp v228, v82 row_ror:8 row_mask:0xf bank_mask:0xf
	v_mov_b32_dpp v229, v83 row_ror:8 row_mask:0xf bank_mask:0xf
	v_mov_b32_dpp v230, v84 row_ror:8 row_mask:0xf bank_mask:0xf
	v_mov_b32_dpp v231, v85 row_ror:8 row_mask:0xf bank_mask:0xf
	v_mov_b32_dpp v212, v86 row_ror:8 row_mask:0xf bank_mask:0xf
	v_mov_b32_dpp v213, v87 row_ror:8 row_mask:0xf bank_mask:0xf
	v_mov_b32_dpp v214, v88 row_ror:8 row_mask:0xf bank_mask:0xf
	v_mov_b32_dpp v215, v89 row_ror:8 row_mask:0xf bank_mask:0xf
	v_cndmask_b32_e64 v86, v86, v228, s[84:85]
	v_cndmask_b32_e64 v87, v87, v229, s[84:85]
	v_cndmask_b32_e64 v88, v88, v230, s[84:85]
	v_cndmask_b32_e64 v89, v89, v231, s[84:85]
	v_cndmask_b32_e64 v82, v212, v82, s[84:85]
	v_cndmask_b32_e64 v83, v213, v83, s[84:85]
	v_cndmask_b32_e64 v84, v214, v84, s[84:85]
	v_cndmask_b32_e64 v85, v215, v85, s[84:85]
	s_mov_b64 s[96:97], 0x50000
	v_lshl_add_u64 v[138:139], v[138:139], 0, s[96:97]
	v_lshl_add_u64 v[140:141], v[140:141], 0, s[96:97]
	global_load_dwordx4 v[180:183], v[138:139], off
	global_load_dwordx4 v[184:187], v[138:139], off offset:512
	global_load_dwordx4 v[188:191], v[140:141], off
	global_load_dwordx4 v[192:195], v[140:141], off offset:512
	s_waitcnt vmcnt(26)
;   __device__ __forceinline__ void operator()(const acc8_t& acc, const pg8::Unit& u, int wr, int wc, int fr, int fq) const {
;     ...
;       for (int m = 0; m < 4; m++) {
;         const int token = (int)EPI_TOKEN(u, ai, m);
;         const float* xr = xrow(p, token);
;         float ss = 0.f;
; #pragma unroll
;         for (int bj = 0; bj < 2; bj++)
; #pragma unroll
;           for (int n = 0; n < 2; n++) {
;             const int f = EPI_COL(u, bj, n);
;             const float4 xv = *(const float4*)(xr + f);
;             const float4 o = make_float4(xv.x + acc[ai][bj][m][n][0], xv.y + acc[ai][bj][m][n][1], xv.z + acc[ai][bj][m][n][2], xv.w + acc[ai][bj][m][n][3]);
;             ss += o.x * o.x + o.y * o.y + o.z * o.z + o.w * o.w;
;             *(float4*)(p.out + O_Y + (size_t)token * 1024 + f) = o;
;             uint2 ob; ob.x = pack2(o.x, o.y); ob.y = pack2(o.z, o.w);
;             *(uint2*)(X1B + (size_t)token * 1024 + f) = ob;
;           }
;         ss = xsum16(ss);
;         ss = xsum32(ss);
;         if (fq == 0) atomicAdd(rss + token, ss);
	v_pk_add_f32 v[196:197], v[196:197], v[94:95]
	v_pk_add_f32 v[198:199], v[198:199], v[96:97]
	v_pk_add_f32 v[204:205], v[204:205], v[90:91]
	v_pk_add_f32 v[206:207], v[206:207], v[92:93]
	v_pk_add_f32 v[200:201], v[200:201], v[86:87]
	v_pk_add_f32 v[202:203], v[202:203], v[88:89]
	v_pk_add_f32 v[208:209], v[208:209], v[82:83]
	v_pk_add_f32 v[210:211], v[210:211], v[84:85]
	global_store_dwordx4 v[142:143], v[196:199], off
	global_store_dwordx4 v[232:233], v[204:207], off
	v_cvt_pk_bf16_f32 v224, v196, v197
	v_cvt_pk_bf16_f32 v225, v198, v199
	v_cvt_pk_bf16_f32 v226, v204, v205
	v_cvt_pk_bf16_f32 v227, v206, v207
	global_store_dwordx2 v[234:235], v[224:225], off
	global_store_dwordx2 v[236:237], v[226:227], off
	global_store_dwordx4 v[142:143], v[200:203], off offset:512
	global_store_dwordx4 v[232:233], v[208:211], off offset:512
	v_cvt_pk_bf16_f32 v220, v200, v201
	v_cvt_pk_bf16_f32 v221, v202, v203
	v_cvt_pk_bf16_f32 v222, v208, v209
	v_cvt_pk_bf16_f32 v223, v210, v211
	global_store_dwordx2 v[234:235], v[220:221], off offset:256
	global_store_dwordx2 v[236:237], v[222:223], off offset:256
	v_mul_f32_e32 v218, v196, v196
	v_mul_f32_e32 v219, v204, v204
	v_fmac_f32_e32 v218, v197, v197
	v_fmac_f32_e32 v219, v205, v205
	v_fmac_f32_e32 v218, v198, v198
	v_fmac_f32_e32 v219, v206, v206
	v_fmac_f32_e32 v218, v199, v199
	v_fmac_f32_e32 v219, v207, v207
	v_fmac_f32_e32 v218, v200, v200
	v_fmac_f32_e32 v219, v208, v208
	v_fmac_f32_e32 v218, v201, v201
	v_fmac_f32_e32 v219, v209, v209
	v_fmac_f32_e32 v218, v202, v202
	v_fmac_f32_e32 v219, v210, v210
	v_fmac_f32_e32 v218, v203, v203
	v_fmac_f32_e32 v219, v211, v211
	v_mov_b32_e32 v216, v218
	v_mov_b32_e32 v217, v219
	s_nop 1
	v_permlane16_swap_b32_e32 v218, v216
	v_permlane16_swap_b32_e32 v219, v217
	v_add_f32_e32 v218, v218, v216
	v_add_f32_e32 v219, v219, v217
	v_mov_b32_e32 v216, v218
	v_mov_b32_e32 v217, v219
	s_nop 1
	v_permlane32_swap_b32_e32 v218, v216
	v_permlane32_swap_b32_e32 v219, v217
	v_add_f32_e32 v218, v218, v216
	v_add_f32_e32 v219, v219, v217
	s_nop 1
	v_add_f32_dpp v216, v218, v218 row_ror:8 row_mask:0xf bank_mask:0xf
	v_add_f32_dpp v217, v219, v219 row_ror:8 row_mask:0xf bank_mask:0xf
	v_cndmask_b32_e64 v216, v216, v217, s[84:85]
	s_and_saveexec_b64 s[82:83], s[4:5]
	global_atomic_add_f32 v163, v216, s[12:13]
	s_or_b64 exec, exec, s[82:83]
	s_mov_b64 s[96:97], 0x10000
	v_lshl_add_u64 v[142:143], v[142:143], 0, s[96:97]
	v_lshl_add_u64 v[232:233], v[232:233], 0, s[96:97]
	s_mov_b64 s[96:97], 0x8000
	v_lshl_add_u64 v[234:235], v[234:235], 0, s[96:97]
	v_lshl_add_u64 v[236:237], v[236:237], 0, s[96:97]
	v_add_u32_e32 v163, 0x40, v163
	v_mov_b32_dpp v228, v74 row_ror:8 row_mask:0xf bank_mask:0xf
	v_mov_b32_dpp v229, v75 row_ror:8 row_mask:0xf bank_mask:0xf
	v_mov_b32_dpp v230, v76 row_ror:8 row_mask:0xf bank_mask:0xf
	v_mov_b32_dpp v231, v77 row_ror:8 row_mask:0xf bank_mask:0xf
	v_mov_b32_dpp v212, v78 row_ror:8 row_mask:0xf bank_mask:0xf
	v_mov_b32_dpp v213, v79 row_ror:8 row_mask:0xf bank_mask:0xf
	v_mov_b32_dpp v214, v80 row_ror:8 row_mask:0xf bank_mask:0xf
	v_mov_b32_dpp v215, v81 row_ror:8 row_mask:0xf bank_mask:0xf
	v_cndmask_b32_e64 v78, v78, v228, s[84:85]
	v_cndmask_b32_e64 v79, v79, v229, s[84:85]
	v_cndmask_b32_e64 v80, v80, v230, s[84:85]
	v_cndmask_b32_e64 v81, v81, v231, s[84:85]
	v_cndmask_b32_e64 v74, v212, v74, s[84:85]
	v_cndmask_b32_e64 v75, v213, v75, s[84:85]
	v_cndmask_b32_e64 v76, v214, v76, s[84:85]
	v_cndmask_b32_e64 v77, v215, v77, s[84:85]
	v_mov_b32_dpp v228, v66 row_ror:8 row_mask:0xf bank_mask:0xf
	v_mov_b32_dpp v229, v67 row_ror:8 row_mask:0xf bank_mask:0xf
	v_mov_b32_dpp v230, v68 row_ror:8 row_mask:0xf bank_mask:0xf
	v_mov_b32_dpp v231, v69 row_ror:8 row_mask:0xf bank_mask:0xf
	v_mov_b32_dpp v212, v70 row_ror:8 row_mask:0xf bank_mask:0xf
	v_mov_b32_dpp v213, v71 row_ror:8 row_mask:0xf bank_mask:0xf
	v_mov_b32_dpp v214, v72 row_ror:8 row_mask:0xf bank_mask:0xf
	v_mov_b32_dpp v215, v73 row_ror:8 row_mask:0xf bank_mask:0xf
	v_cndmask_b32_e64 v70, v70, v228, s[84:85]
	v_cndmask_b32_e64 v71, v71, v229, s[84:85]
	v_cndmask_b32_e64 v72, v72, v230, s[84:85]
	v_cndmask_b32_e64 v73, v73, v231, s[84:85]
	v_cndmask_b32_e64 v66, v212, v66, s[84:85]
	v_cndmask_b32_e64 v67, v213, v67, s[84:85]
	v_cndmask_b32_e64 v68, v214, v68, s[84:85]
	v_cndmask_b32_e64 v69, v215, v69, s[84:85]
	s_mov_b64 s[96:97], 0x10000
	v_lshl_add_u64 v[138:139], v[138:139], 0, s[96:97]
	v_lshl_add_u64 v[140:141], v[140:141], 0, s[96:97]
	global_load_dwordx4 v[196:199], v[138:139], off
	global_load_dwordx4 v[200:203], v[138:139], off offset:512
	global_load_dwordx4 v[204:207], v[140:141], off
	global_load_dwordx4 v[208:211], v[140:141], off offset:512
	s_waitcnt vmcnt(26)
;   __device__ __forceinline__ void operator()(const acc8_t& acc, const pg8::Unit& u, int wr, int wc, int fr, int fq) const {
;     ...
;       for (int m = 0; m < 4; m++) {
;         const int token = (int)EPI_TOKEN(u, ai, m);
;         const float* xr = xrow(p, token);
;         float ss = 0.f;
; #pragma unroll
;         for (int bj = 0; bj < 2; bj++)
; #pragma unroll
;           for (int n = 0; n < 2; n++) {
;             const int f = EPI_COL(u, bj, n);
;             const float4 xv = *(const float4*)(xr + f);
;             const float4 o = make_float4(xv.x + acc[ai][bj][m][n][0], xv.y + acc[ai][bj][m][n][1], xv.z + acc[ai][bj][m][n][2], xv.w + acc[ai][bj][m][n][3]);
;             ss += o.x * o.x + o.y * o.y + o.z * o.z + o.w * o.w;
;             *(float4*)(p.out + O_Y + (size_t)token * 1024 + f) = o;
;             uint2 ob; ob.x = pack2(o.x, o.y); ob.y = pack2(o.z, o.w);
;             *(uint2*)(X1B + (size_t)token * 1024 + f) = ob;
;           }
;         ss = xsum16(ss);
;         ss = xsum32(ss);
;         if (fq == 0) atomicAdd(rss + token, ss);
	v_pk_add_f32 v[164:165], v[164:165], v[78:79]
	v_pk_add_f32 v[166:167], v[166:167], v[80:81]
	v_pk_add_f32 v[172:173], v[172:173], v[74:75]
	v_pk_add_f32 v[174:175], v[174:175], v[76:77]
	v_pk_add_f32 v[168:169], v[168:169], v[70:71]
	v_pk_add_f32 v[170:171], v[170:171], v[72:73]
	v_pk_add_f32 v[176:177], v[176:177], v[66:67]
	v_pk_add_f32 v[178:179], v[178:179], v[68:69]
	global_store_dwordx4 v[142:143], v[164:167], off
	global_store_dwordx4 v[232:233], v[172:175], off
	v_cvt_pk_bf16_f32 v224, v164, v165
	v_cvt_pk_bf16_f32 v225, v166, v167
	v_cvt_pk_bf16_f32 v226, v172, v173
	v_cvt_pk_bf16_f32 v227, v174, v175
	global_store_dwordx2 v[234:235], v[224:225], off
	global_store_dwordx2 v[236:237], v[226:227], off
	global_store_dwordx4 v[142:143], v[168:171], off offset:512
	global_store_dwordx4 v[232:233], v[176:179], off offset:512
	v_cvt_pk_bf16_f32 v220, v168, v169
	v_cvt_pk_bf16_f32 v221, v170, v171
	v_cvt_pk_bf16_f32 v222, v176, v177
	v_cvt_pk_bf16_f32 v223, v178, v179
	global_store_dwordx2 v[234:235], v[220:221], off offset:256
	global_store_dwordx2 v[236:237], v[222:223], off offset:256
	v_mul_f32_e32 v218, v164, v164
	v_mul_f32_e32 v219, v172, v172
	v_fmac_f32_e32 v218, v165, v165
	v_fmac_f32_e32 v219, v173, v173
	v_fmac_f32_e32 v218, v166, v166
	v_fmac_f32_e32 v219, v174, v174
	v_fmac_f32_e32 v218, v167, v167
	v_fmac_f32_e32 v219, v175, v175
	v_fmac_f32_e32 v218, v168, v168
	v_fmac_f32_e32 v219, v176, v176
	v_fmac_f32_e32 v218, v169, v169
	v_fmac_f32_e32 v219, v177, v177
	v_fmac_f32_e32 v218, v170, v170
	v_fmac_f32_e32 v219, v178, v178
	v_fmac_f32_e32 v218, v171, v171
	v_fmac_f32_e32 v219, v179, v179
	v_mov_b32_e32 v216, v218
	v_mov_b32_e32 v217, v219
	s_nop 1
	v_permlane16_swap_b32_e32 v218, v216
	v_permlane16_swap_b32_e32 v219, v217
	v_add_f32_e32 v218, v218, v216
	v_add_f32_e32 v219, v219, v217
	v_mov_b32_e32 v216, v218
	v_mov_b32_e32 v217, v219
	s_nop 1
	v_permlane32_swap_b32_e32 v218, v216
	v_permlane32_swap_b32_e32 v219, v217
	v_add_f32_e32 v218, v218, v216
	v_add_f32_e32 v219, v219, v217
	s_nop 1
	v_add_f32_dpp v216, v218, v218 row_ror:8 row_mask:0xf bank_mask:0xf
	v_add_f32_dpp v217, v219, v219 row_ror:8 row_mask:0xf bank_mask:0xf
	v_cndmask_b32_e64 v216, v216, v217, s[84:85]
	s_and_saveexec_b64 s[82:83], s[4:5]
	global_atomic_add_f32 v163, v216, s[12:13]
	s_or_b64 exec, exec, s[82:83]
	s_mov_b64 s[96:97], 0x50000
	v_lshl_add_u64 v[142:143], v[142:143], 0, s[96:97]
	v_lshl_add_u64 v[232:233], v[232:233], 0, s[96:97]
	s_mov_b64 s[96:97], 0x28000
	v_lshl_add_u64 v[234:235], v[234:235], 0, s[96:97]
	v_lshl_add_u64 v[236:237], v[236:237], 0, s[96:97]
	v_add_u32_e32 v163, 0x140, v163
	v_mov_b32_dpp v228, v58 row_ror:8 row_mask:0xf bank_mask:0xf
	v_mov_b32_dpp v229, v59 row_ror:8 row_mask:0xf bank_mask:0xf
	v_mov_b32_dpp v230, v60 row_ror:8 row_mask:0xf bank_mask:0xf
	v_mov_b32_dpp v231, v61 row_ror:8 row_mask:0xf bank_mask:0xf
	v_mov_b32_dpp v212, v62 row_ror:8 row_mask:0xf bank_mask:0xf
	v_mov_b32_dpp v213, v63 row_ror:8 row_mask:0xf bank_mask:0xf
	v_mov_b32_dpp v214, v64 row_ror:8 row_mask:0xf bank_mask:0xf
	v_mov_b32_dpp v215, v65 row_ror:8 row_mask:0xf bank_mask:0xf
	v_cndmask_b32_e64 v62, v62, v228, s[84:85]
	v_cndmask_b32_e64 v63, v63, v229, s[84:85]
	v_cndmask_b32_e64 v64, v64, v230, s[84:85]
	v_cndmask_b32_e64 v65, v65, v231, s[84:85]
	v_cndmask_b32_e64 v58, v212, v58, s[84:85]
	v_cndmask_b32_e64 v59, v213, v59, s[84:85]
	v_cndmask_b32_e64 v60, v214, v60, s[84:85]
	v_cndmask_b32_e64 v61, v215, v61, s[84:85]
	v_mov_b32_dpp v228, v50 row_ror:8 row_mask:0xf bank_mask:0xf
	v_mov_b32_dpp v229, v51 row_ror:8 row_mask:0xf bank_mask:0xf
	v_mov_b32_dpp v230, v52 row_ror:8 row_mask:0xf bank_mask:0xf
	v_mov_b32_dpp v231, v53 row_ror:8 row_mask:0xf bank_mask:0xf
	v_mov_b32_dpp v212, v54 row_ror:8 row_mask:0xf bank_mask:0xf
	v_mov_b32_dpp v213, v55 row_ror:8 row_mask:0xf bank_mask:0xf
	v_mov_b32_dpp v214, v56 row_ror:8 row_mask:0xf bank_mask:0xf
	v_mov_b32_dpp v215, v57 row_ror:8 row_mask:0xf bank_mask:0xf
	v_cndmask_b32_e64 v54, v54, v228, s[84:85]
	v_cndmask_b32_e64 v55, v55, v229, s[84:85]
	v_cndmask_b32_e64 v56, v56, v230, s[84:85]
	v_cndmask_b32_e64 v57, v57, v231, s[84:85]
	v_cndmask_b32_e64 v50, v212, v50, s[84:85]
	v_cndmask_b32_e64 v51, v213, v51, s[84:85]
	v_cndmask_b32_e64 v52, v214, v52, s[84:85]
	v_cndmask_b32_e64 v53, v215, v53, s[84:85]
	s_mov_b64 s[96:97], 0x10000
	v_lshl_add_u64 v[138:139], v[138:139], 0, s[96:97]
	v_lshl_add_u64 v[140:141], v[140:141], 0, s[96:97]
	global_load_dwordx4 v[164:167], v[138:139], off
	global_load_dwordx4 v[168:171], v[138:139], off offset:512
	global_load_dwordx4 v[172:175], v[140:141], off
	global_load_dwordx4 v[176:179], v[140:141], off offset:512
	s_waitcnt vmcnt(26)
;   __device__ __forceinline__ void operator()(const acc8_t& acc, const pg8::Unit& u, int wr, int wc, int fr, int fq) const {
;     ...
;       for (int m = 0; m < 4; m++) {
;         const int token = (int)EPI_TOKEN(u, ai, m);
;         const float* xr = xrow(p, token);
;         float ss = 0.f;
; #pragma unroll
;         for (int bj = 0; bj < 2; bj++)
; #pragma unroll
;           for (int n = 0; n < 2; n++) {
;             const int f = EPI_COL(u, bj, n);
;             const float4 xv = *(const float4*)(xr + f);
;             const float4 o = make_float4(xv.x + acc[ai][bj][m][n][0], xv.y + acc[ai][bj][m][n][1], xv.z + acc[ai][bj][m][n][2], xv.w + acc[ai][bj][m][n][3]);
;             ss += o.x * o.x + o.y * o.y + o.z * o.z + o.w * o.w;
;             *(float4*)(p.out + O_Y + (size_t)token * 1024 + f) = o;
;             uint2 ob; ob.x = pack2(o.x, o.y); ob.y = pack2(o.z, o.w);
;             *(uint2*)(X1B + (size_t)token * 1024 + f) = ob;
;           }
;         ss = xsum16(ss);
;         ss = xsum32(ss);
;         if (fq == 0) atomicAdd(rss + token, ss);
	v_pk_add_f32 v[180:181], v[180:181], v[62:63]
	v_pk_add_f32 v[182:183], v[182:183], v[64:65]
	v_pk_add_f32 v[188:189], v[188:189], v[58:59]
	v_pk_add_f32 v[190:191], v[190:191], v[60:61]
	v_pk_add_f32 v[184:185], v[184:185], v[54:55]
	v_pk_add_f32 v[186:187], v[186:187], v[56:57]
	v_pk_add_f32 v[192:193], v[192:193], v[50:51]
	v_pk_add_f32 v[194:195], v[194:195], v[52:53]
	global_store_dwordx4 v[142:143], v[180:183], off
	global_store_dwordx4 v[232:233], v[188:191], off
	v_cvt_pk_bf16_f32 v224, v180, v181
	v_cvt_pk_bf16_f32 v225, v182, v183
	v_cvt_pk_bf16_f32 v226, v188, v189
	v_cvt_pk_bf16_f32 v227, v190, v191
	global_store_dwordx2 v[234:235], v[224:225], off
	global_store_dwordx2 v[236:237], v[226:227], off
	global_store_dwordx4 v[142:143], v[184:187], off offset:512
	global_store_dwordx4 v[232:233], v[192:195], off offset:512
	v_cvt_pk_bf16_f32 v220, v184, v185
	v_cvt_pk_bf16_f32 v221, v186, v187
	v_cvt_pk_bf16_f32 v222, v192, v193
	v_cvt_pk_bf16_f32 v223, v194, v195
	global_store_dwordx2 v[234:235], v[220:221], off offset:256
	global_store_dwordx2 v[236:237], v[222:223], off offset:256
	v_mul_f32_e32 v218, v180, v180
	v_mul_f32_e32 v219, v188, v188
	v_fmac_f32_e32 v218, v181, v181
	v_fmac_f32_e32 v219, v189, v189
	v_fmac_f32_e32 v218, v182, v182
	v_fmac_f32_e32 v219, v190, v190
	v_fmac_f32_e32 v218, v183, v183
	v_fmac_f32_e32 v219, v191, v191
	v_fmac_f32_e32 v218, v184, v184
	v_fmac_f32_e32 v219, v192, v192
	v_fmac_f32_e32 v218, v185, v185
	v_fmac_f32_e32 v219, v193, v193
	v_fmac_f32_e32 v218, v186, v186
	v_fmac_f32_e32 v219, v194, v194
	v_fmac_f32_e32 v218, v187, v187
	v_fmac_f32_e32 v219, v195, v195
	v_mov_b32_e32 v216, v218
	v_mov_b32_e32 v217, v219
	s_nop 1
	v_permlane16_swap_b32_e32 v218, v216
	v_permlane16_swap_b32_e32 v219, v217
	v_add_f32_e32 v218, v218, v216
	v_add_f32_e32 v219, v219, v217
	v_mov_b32_e32 v216, v218
	v_mov_b32_e32 v217, v219
	s_nop 1
	v_permlane32_swap_b32_e32 v218, v216
	v_permlane32_swap_b32_e32 v219, v217
	v_add_f32_e32 v218, v218, v216
	v_add_f32_e32 v219, v219, v217
	s_nop 1
	v_add_f32_dpp v216, v218, v218 row_ror:8 row_mask:0xf bank_mask:0xf
	v_add_f32_dpp v217, v219, v219 row_ror:8 row_mask:0xf bank_mask:0xf
	v_cndmask_b32_e64 v216, v216, v217, s[84:85]
	s_and_saveexec_b64 s[82:83], s[4:5]
	global_atomic_add_f32 v163, v216, s[12:13]
	s_or_b64 exec, exec, s[82:83]
	s_mov_b64 s[96:97], 0x10000
	v_lshl_add_u64 v[142:143], v[142:143], 0, s[96:97]
	v_lshl_add_u64 v[232:233], v[232:233], 0, s[96:97]
	s_mov_b64 s[96:97], 0x8000
	v_lshl_add_u64 v[234:235], v[234:235], 0, s[96:97]
	v_lshl_add_u64 v[236:237], v[236:237], 0, s[96:97]
	v_add_u32_e32 v163, 0x40, v163
	v_mov_b32_dpp v228, v42 row_ror:8 row_mask:0xf bank_mask:0xf
	v_mov_b32_dpp v229, v43 row_ror:8 row_mask:0xf bank_mask:0xf
	v_mov_b32_dpp v230, v44 row_ror:8 row_mask:0xf bank_mask:0xf
	v_mov_b32_dpp v231, v45 row_ror:8 row_mask:0xf bank_mask:0xf
	v_mov_b32_dpp v212, v46 row_ror:8 row_mask:0xf bank_mask:0xf
	v_mov_b32_dpp v213, v47 row_ror:8 row_mask:0xf bank_mask:0xf
	v_mov_b32_dpp v214, v48 row_ror:8 row_mask:0xf bank_mask:0xf
	v_mov_b32_dpp v215, v49 row_ror:8 row_mask:0xf bank_mask:0xf
	v_cndmask_b32_e64 v46, v46, v228, s[84:85]
	v_cndmask_b32_e64 v47, v47, v229, s[84:85]
	v_cndmask_b32_e64 v48, v48, v230, s[84:85]
	v_cndmask_b32_e64 v49, v49, v231, s[84:85]
	v_cndmask_b32_e64 v42, v212, v42, s[84:85]
	v_cndmask_b32_e64 v43, v213, v43, s[84:85]
	v_cndmask_b32_e64 v44, v214, v44, s[84:85]
	v_cndmask_b32_e64 v45, v215, v45, s[84:85]
	v_mov_b32_dpp v228, v34 row_ror:8 row_mask:0xf bank_mask:0xf
	v_mov_b32_dpp v229, v35 row_ror:8 row_mask:0xf bank_mask:0xf
	v_mov_b32_dpp v230, v36 row_ror:8 row_mask:0xf bank_mask:0xf
	v_mov_b32_dpp v231, v37 row_ror:8 row_mask:0xf bank_mask:0xf
	v_mov_b32_dpp v212, v38 row_ror:8 row_mask:0xf bank_mask:0xf
	v_mov_b32_dpp v213, v39 row_ror:8 row_mask:0xf bank_mask:0xf
	v_mov_b32_dpp v214, v40 row_ror:8 row_mask:0xf bank_mask:0xf
	v_mov_b32_dpp v215, v41 row_ror:8 row_mask:0xf bank_mask:0xf
	v_cndmask_b32_e64 v38, v38, v228, s[84:85]
	v_cndmask_b32_e64 v39, v39, v229, s[84:85]
	v_cndmask_b32_e64 v40, v40, v230, s[84:85]
	v_cndmask_b32_e64 v41, v41, v231, s[84:85]
	v_cndmask_b32_e64 v34, v212, v34, s[84:85]
	v_cndmask_b32_e64 v35, v213, v35, s[84:85]
	v_cndmask_b32_e64 v36, v214, v36, s[84:85]
	v_cndmask_b32_e64 v37, v215, v37, s[84:85]
	s_mov_b64 s[96:97], 0x10000
	v_lshl_add_u64 v[138:139], v[138:139], 0, s[96:97]
	v_lshl_add_u64 v[140:141], v[140:141], 0, s[96:97]
	global_load_dwordx4 v[180:183], v[138:139], off
	global_load_dwordx4 v[184:187], v[138:139], off offset:512
	global_load_dwordx4 v[188:191], v[140:141], off
	global_load_dwordx4 v[192:195], v[140:141], off offset:512
	s_waitcnt vmcnt(26)
;   __device__ __forceinline__ void operator()(const acc8_t& acc, const pg8::Unit& u, int wr, int wc, int fr, int fq) const {
;     ...
;       for (int m = 0; m < 4; m++) {
;         const int token = (int)EPI_TOKEN(u, ai, m);
;         const float* xr = xrow(p, token);
;         float ss = 0.f;
; #pragma unroll
;         for (int bj = 0; bj < 2; bj++)
; #pragma unroll
;           for (int n = 0; n < 2; n++) {
;             const int f = EPI_COL(u, bj, n);
;             const float4 xv = *(const float4*)(xr + f);
;             const float4 o = make_float4(xv.x + acc[ai][bj][m][n][0], xv.y + acc[ai][bj][m][n][1], xv.z + acc[ai][bj][m][n][2], xv.w + acc[ai][bj][m][n][3]);
;             ss += o.x * o.x + o.y * o.y + o.z * o.z + o.w * o.w;
;             *(float4*)(p.out + O_Y + (size_t)token * 1024 + f) = o;
;             uint2 ob; ob.x = pack2(o.x, o.y); ob.y = pack2(o.z, o.w);
;             *(uint2*)(X1B + (size_t)token * 1024 + f) = ob;
;           }
;         ss = xsum16(ss);
;         ss = xsum32(ss);
;         if (fq == 0) atomicAdd(rss + token, ss);
	v_pk_add_f32 v[196:197], v[196:197], v[46:47]
	v_pk_add_f32 v[198:199], v[198:199], v[48:49]
	v_pk_add_f32 v[204:205], v[204:205], v[42:43]
	v_pk_add_f32 v[206:207], v[206:207], v[44:45]
	v_pk_add_f32 v[200:201], v[200:201], v[38:39]
	v_pk_add_f32 v[202:203], v[202:203], v[40:41]
	v_pk_add_f32 v[208:209], v[208:209], v[34:35]
	v_pk_add_f32 v[210:211], v[210:211], v[36:37]
	global_store_dwordx4 v[142:143], v[196:199], off
	global_store_dwordx4 v[232:233], v[204:207], off
	v_cvt_pk_bf16_f32 v224, v196, v197
	v_cvt_pk_bf16_f32 v225, v198, v199
	v_cvt_pk_bf16_f32 v226, v204, v205
	v_cvt_pk_bf16_f32 v227, v206, v207
	global_store_dwordx2 v[234:235], v[224:225], off
	global_store_dwordx2 v[236:237], v[226:227], off
	global_store_dwordx4 v[142:143], v[200:203], off offset:512
	global_store_dwordx4 v[232:233], v[208:211], off offset:512
	v_cvt_pk_bf16_f32 v220, v200, v201
	v_cvt_pk_bf16_f32 v221, v202, v203
	v_cvt_pk_bf16_f32 v222, v208, v209
	v_cvt_pk_bf16_f32 v223, v210, v211
	global_store_dwordx2 v[234:235], v[220:221], off offset:256
	global_store_dwordx2 v[236:237], v[222:223], off offset:256
	v_mul_f32_e32 v218, v196, v196
	v_mul_f32_e32 v219, v204, v204
	v_fmac_f32_e32 v218, v197, v197
	v_fmac_f32_e32 v219, v205, v205
	v_fmac_f32_e32 v218, v198, v198
	v_fmac_f32_e32 v219, v206, v206
	v_fmac_f32_e32 v218, v199, v199
	v_fmac_f32_e32 v219, v207, v207
	v_fmac_f32_e32 v218, v200, v200
	v_fmac_f32_e32 v219, v208, v208
	v_fmac_f32_e32 v218, v201, v201
	v_fmac_f32_e32 v219, v209, v209
	v_fmac_f32_e32 v218, v202, v202
	v_fmac_f32_e32 v219, v210, v210
	v_fmac_f32_e32 v218, v203, v203
	v_fmac_f32_e32 v219, v211, v211
	v_mov_b32_e32 v216, v218
	v_mov_b32_e32 v217, v219
	s_nop 1
	v_permlane16_swap_b32_e32 v218, v216
	v_permlane16_swap_b32_e32 v219, v217
	v_add_f32_e32 v218, v218, v216
	v_add_f32_e32 v219, v219, v217
	v_mov_b32_e32 v216, v218
	v_mov_b32_e32 v217, v219
	s_nop 1
	v_permlane32_swap_b32_e32 v218, v216
	v_permlane32_swap_b32_e32 v219, v217
	v_add_f32_e32 v218, v218, v216
	v_add_f32_e32 v219, v219, v217
	s_nop 1
	v_add_f32_dpp v216, v218, v218 row_ror:8 row_mask:0xf bank_mask:0xf
	v_add_f32_dpp v217, v219, v219 row_ror:8 row_mask:0xf bank_mask:0xf
	v_cndmask_b32_e64 v216, v216, v217, s[84:85]
	s_and_saveexec_b64 s[82:83], s[4:5]
	global_atomic_add_f32 v163, v216, s[12:13]
	s_or_b64 exec, exec, s[82:83]
	s_mov_b64 s[96:97], 0x10000
	v_lshl_add_u64 v[142:143], v[142:143], 0, s[96:97]
	v_lshl_add_u64 v[232:233], v[232:233], 0, s[96:97]
	s_mov_b64 s[96:97], 0x8000
	v_lshl_add_u64 v[234:235], v[234:235], 0, s[96:97]
	v_lshl_add_u64 v[236:237], v[236:237], 0, s[96:97]
	v_add_u32_e32 v163, 0x40, v163
	v_mov_b32_dpp v228, v26 row_ror:8 row_mask:0xf bank_mask:0xf
	v_mov_b32_dpp v229, v27 row_ror:8 row_mask:0xf bank_mask:0xf
	v_mov_b32_dpp v230, v28 row_ror:8 row_mask:0xf bank_mask:0xf
	v_mov_b32_dpp v231, v29 row_ror:8 row_mask:0xf bank_mask:0xf
	v_mov_b32_dpp v212, v30 row_ror:8 row_mask:0xf bank_mask:0xf
	v_mov_b32_dpp v213, v31 row_ror:8 row_mask:0xf bank_mask:0xf
	v_mov_b32_dpp v214, v32 row_ror:8 row_mask:0xf bank_mask:0xf
	v_mov_b32_dpp v215, v33 row_ror:8 row_mask:0xf bank_mask:0xf
	v_cndmask_b32_e64 v30, v30, v228, s[84:85]
	v_cndmask_b32_e64 v31, v31, v229, s[84:85]
	v_cndmask_b32_e64 v32, v32, v230, s[84:85]
	v_cndmask_b32_e64 v33, v33, v231, s[84:85]
	v_cndmask_b32_e64 v26, v212, v26, s[84:85]
	v_cndmask_b32_e64 v27, v213, v27, s[84:85]
	v_cndmask_b32_e64 v28, v214, v28, s[84:85]
	v_cndmask_b32_e64 v29, v215, v29, s[84:85]
	v_mov_b32_dpp v228, v18 row_ror:8 row_mask:0xf bank_mask:0xf
	v_mov_b32_dpp v229, v19 row_ror:8 row_mask:0xf bank_mask:0xf
	v_mov_b32_dpp v230, v20 row_ror:8 row_mask:0xf bank_mask:0xf
	v_mov_b32_dpp v231, v21 row_ror:8 row_mask:0xf bank_mask:0xf
	v_mov_b32_dpp v212, v22 row_ror:8 row_mask:0xf bank_mask:0xf
	v_mov_b32_dpp v213, v23 row_ror:8 row_mask:0xf bank_mask:0xf
	v_mov_b32_dpp v214, v24 row_ror:8 row_mask:0xf bank_mask:0xf
	v_mov_b32_dpp v215, v25 row_ror:8 row_mask:0xf bank_mask:0xf
	v_cndmask_b32_e64 v22, v22, v228, s[84:85]
	v_cndmask_b32_e64 v23, v23, v229, s[84:85]
	v_cndmask_b32_e64 v24, v24, v230, s[84:85]
	v_cndmask_b32_e64 v25, v25, v231, s[84:85]
	v_cndmask_b32_e64 v18, v212, v18, s[84:85]
	v_cndmask_b32_e64 v19, v213, v19, s[84:85]
	v_cndmask_b32_e64 v20, v214, v20, s[84:85]
	v_cndmask_b32_e64 v21, v215, v21, s[84:85]
	s_waitcnt vmcnt(22)
;   __device__ __forceinline__ void operator()(const acc8_t& acc, const pg8::Unit& u, int wr, int wc, int fr, int fq) const {
;     ...
;       for (int m = 0; m < 4; m++) {
;         const int token = (int)EPI_TOKEN(u, ai, m);
;         const float* xr = xrow(p, token);
;         float ss = 0.f;
; #pragma unroll
;         for (int bj = 0; bj < 2; bj++)
; #pragma unroll
;           for (int n = 0; n < 2; n++) {
;             const int f = EPI_COL(u, bj, n);
;             const float4 xv = *(const float4*)(xr + f);
;             const float4 o = make_float4(xv.x + acc[ai][bj][m][n][0], xv.y + acc[ai][bj][m][n][1], xv.z + acc[ai][bj][m][n][2], xv.w + acc[ai][bj][m][n][3]);
;             ss += o.x * o.x + o.y * o.y + o.z * o.z + o.w * o.w;
;             *(float4*)(p.out + O_Y + (size_t)token * 1024 + f) = o;
;             uint2 ob; ob.x = pack2(o.x, o.y); ob.y = pack2(o.z, o.w);
;             *(uint2*)(X1B + (size_t)token * 1024 + f) = ob;
;           }
;         ss = xsum16(ss);
;         ss = xsum32(ss);
;         if (fq == 0) atomicAdd(rss + token, ss);
	v_pk_add_f32 v[164:165], v[164:165], v[30:31]
	v_pk_add_f32 v[166:167], v[166:167], v[32:33]
	v_pk_add_f32 v[172:173], v[172:173], v[26:27]
	v_pk_add_f32 v[174:175], v[174:175], v[28:29]
	v_pk_add_f32 v[168:169], v[168:169], v[22:23]
	v_pk_add_f32 v[170:171], v[170:171], v[24:25]
	v_pk_add_f32 v[176:177], v[176:177], v[18:19]
	v_pk_add_f32 v[178:179], v[178:179], v[20:21]
	global_store_dwordx4 v[142:143], v[164:167], off
	global_store_dwordx4 v[232:233], v[172:175], off
	v_cvt_pk_bf16_f32 v224, v164, v165
	v_cvt_pk_bf16_f32 v225, v166, v167
	v_cvt_pk_bf16_f32 v226, v172, v173
	v_cvt_pk_bf16_f32 v227, v174, v175
	global_store_dwordx2 v[234:235], v[224:225], off
	global_store_dwordx2 v[236:237], v[226:227], off
	global_store_dwordx4 v[142:143], v[168:171], off offset:512
	global_store_dwordx4 v[232:233], v[176:179], off offset:512
	v_cvt_pk_bf16_f32 v220, v168, v169
	v_cvt_pk_bf16_f32 v221, v170, v171
	v_cvt_pk_bf16_f32 v222, v176, v177
	v_cvt_pk_bf16_f32 v223, v178, v179
	global_store_dwordx2 v[234:235], v[220:221], off offset:256
	global_store_dwordx2 v[236:237], v[222:223], off offset:256
	v_mul_f32_e32 v218, v164, v164
	v_mul_f32_e32 v219, v172, v172
	v_fmac_f32_e32 v218, v165, v165
	v_fmac_f32_e32 v219, v173, v173
	v_fmac_f32_e32 v218, v166, v166
	v_fmac_f32_e32 v219, v174, v174
	v_fmac_f32_e32 v218, v167, v167
	v_fmac_f32_e32 v219, v175, v175
	v_fmac_f32_e32 v218, v168, v168
	v_fmac_f32_e32 v219, v176, v176
	v_fmac_f32_e32 v218, v169, v169
	v_fmac_f32_e32 v219, v177, v177
	v_fmac_f32_e32 v218, v170, v170
	v_fmac_f32_e32 v219, v178, v178
	v_fmac_f32_e32 v218, v171, v171
	v_fmac_f32_e32 v219, v179, v179
	v_mov_b32_e32 v216, v218
	v_mov_b32_e32 v217, v219
	s_nop 1
	v_permlane16_swap_b32_e32 v218, v216
	v_permlane16_swap_b32_e32 v219, v217
	v_add_f32_e32 v218, v218, v216
	v_add_f32_e32 v219, v219, v217
	v_mov_b32_e32 v216, v218
	v_mov_b32_e32 v217, v219
	s_nop 1
	v_permlane32_swap_b32_e32 v218, v216
	v_permlane32_swap_b32_e32 v219, v217
	v_add_f32_e32 v218, v218, v216
	v_add_f32_e32 v219, v219, v217
	s_nop 1
	v_add_f32_dpp v216, v218, v218 row_ror:8 row_mask:0xf bank_mask:0xf
	v_add_f32_dpp v217, v219, v219 row_ror:8 row_mask:0xf bank_mask:0xf
	v_cndmask_b32_e64 v216, v216, v217, s[84:85]
	s_and_saveexec_b64 s[82:83], s[4:5]
	global_atomic_add_f32 v163, v216, s[12:13]
	s_or_b64 exec, exec, s[82:83]
	s_mov_b64 s[96:97], 0x10000
	v_lshl_add_u64 v[142:143], v[142:143], 0, s[96:97]
	v_lshl_add_u64 v[232:233], v[232:233], 0, s[96:97]
	s_mov_b64 s[96:97], 0x8000
	v_lshl_add_u64 v[234:235], v[234:235], 0, s[96:97]
	v_lshl_add_u64 v[236:237], v[236:237], 0, s[96:97]
	v_add_u32_e32 v163, 0x40, v163
	v_mov_b32_dpp v228, v10 row_ror:8 row_mask:0xf bank_mask:0xf
	v_mov_b32_dpp v229, v11 row_ror:8 row_mask:0xf bank_mask:0xf
	v_mov_b32_dpp v230, v12 row_ror:8 row_mask:0xf bank_mask:0xf
	v_mov_b32_dpp v231, v13 row_ror:8 row_mask:0xf bank_mask:0xf
	v_mov_b32_dpp v212, v14 row_ror:8 row_mask:0xf bank_mask:0xf
	v_mov_b32_dpp v213, v15 row_ror:8 row_mask:0xf bank_mask:0xf
	v_mov_b32_dpp v214, v16 row_ror:8 row_mask:0xf bank_mask:0xf
	v_mov_b32_dpp v215, v17 row_ror:8 row_mask:0xf bank_mask:0xf
	v_cndmask_b32_e64 v14, v14, v228, s[84:85]
	v_cndmask_b32_e64 v15, v15, v229, s[84:85]
	v_cndmask_b32_e64 v16, v16, v230, s[84:85]
	v_cndmask_b32_e64 v17, v17, v231, s[84:85]
	v_cndmask_b32_e64 v10, v212, v10, s[84:85]
	v_cndmask_b32_e64 v11, v213, v11, s[84:85]
	v_cndmask_b32_e64 v12, v214, v12, s[84:85]
	v_cndmask_b32_e64 v13, v215, v13, s[84:85]
	v_mov_b32_dpp v228, v2 row_ror:8 row_mask:0xf bank_mask:0xf
	v_mov_b32_dpp v229, v3 row_ror:8 row_mask:0xf bank_mask:0xf
	v_mov_b32_dpp v230, v4 row_ror:8 row_mask:0xf bank_mask:0xf
	v_mov_b32_dpp v231, v5 row_ror:8 row_mask:0xf bank_mask:0xf
	v_mov_b32_dpp v212, v6 row_ror:8 row_mask:0xf bank_mask:0xf
	v_mov_b32_dpp v213, v7 row_ror:8 row_mask:0xf bank_mask:0xf
	v_mov_b32_dpp v214, v8 row_ror:8 row_mask:0xf bank_mask:0xf
	v_mov_b32_dpp v215, v9 row_ror:8 row_mask:0xf bank_mask:0xf
	v_cndmask_b32_e64 v6, v6, v228, s[84:85]
	v_cndmask_b32_e64 v7, v7, v229, s[84:85]
	v_cndmask_b32_e64 v8, v8, v230, s[84:85]
	v_cndmask_b32_e64 v9, v9, v231, s[84:85]
	v_cndmask_b32_e64 v2, v212, v2, s[84:85]
	v_cndmask_b32_e64 v3, v213, v3, s[84:85]
	v_cndmask_b32_e64 v4, v214, v4, s[84:85]
	v_cndmask_b32_e64 v5, v215, v5, s[84:85]
	s_waitcnt vmcnt(18)
	v_pk_add_f32 v[180:181], v[180:181], v[14:15]
	v_pk_add_f32 v[182:183], v[182:183], v[16:17]
	v_pk_add_f32 v[188:189], v[188:189], v[10:11]
	v_pk_add_f32 v[190:191], v[190:191], v[12:13]
	v_pk_add_f32 v[184:185], v[184:185], v[6:7]
	v_pk_add_f32 v[186:187], v[186:187], v[8:9]
	v_pk_add_f32 v[192:193], v[192:193], v[2:3]
	v_pk_add_f32 v[194:195], v[194:195], v[4:5]
	global_store_dwordx4 v[142:143], v[180:183], off
	global_store_dwordx4 v[232:233], v[188:191], off
	v_cvt_pk_bf16_f32 v224, v180, v181
	v_cvt_pk_bf16_f32 v225, v182, v183
	v_cvt_pk_bf16_f32 v226, v188, v189
	v_cvt_pk_bf16_f32 v227, v190, v191
	global_store_dwordx2 v[234:235], v[224:225], off
	global_store_dwordx2 v[236:237], v[226:227], off
	global_store_dwordx4 v[142:143], v[184:187], off offset:512
	global_store_dwordx4 v[232:233], v[192:195], off offset:512
	v_cvt_pk_bf16_f32 v220, v184, v185
	v_cvt_pk_bf16_f32 v221, v186, v187
	v_cvt_pk_bf16_f32 v222, v192, v193
	v_cvt_pk_bf16_f32 v223, v194, v195
	global_store_dwordx2 v[234:235], v[220:221], off offset:256
	global_store_dwordx2 v[236:237], v[222:223], off offset:256
	v_mul_f32_e32 v218, v180, v180
	v_mul_f32_e32 v219, v188, v188
	v_fmac_f32_e32 v218, v181, v181
	v_fmac_f32_e32 v219, v189, v189
	v_fmac_f32_e32 v218, v182, v182
	v_fmac_f32_e32 v219, v190, v190
	v_fmac_f32_e32 v218, v183, v183
	v_fmac_f32_e32 v219, v191, v191
	v_fmac_f32_e32 v218, v184, v184
	v_fmac_f32_e32 v219, v192, v192
	v_fmac_f32_e32 v218, v185, v185
	v_fmac_f32_e32 v219, v193, v193
	v_fmac_f32_e32 v218, v186, v186
	v_fmac_f32_e32 v219, v194, v194
	v_fmac_f32_e32 v218, v187, v187
	v_fmac_f32_e32 v219, v195, v195
	v_mov_b32_e32 v216, v218
	v_mov_b32_e32 v217, v219
	s_nop 1
	v_permlane16_swap_b32_e32 v218, v216
	v_permlane16_swap_b32_e32 v219, v217
	v_add_f32_e32 v218, v218, v216
	v_add_f32_e32 v219, v219, v217
	v_mov_b32_e32 v216, v218
	v_mov_b32_e32 v217, v219
	s_nop 1
	v_permlane32_swap_b32_e32 v218, v216
	v_permlane32_swap_b32_e32 v219, v217
	v_add_f32_e32 v218, v218, v216
	v_add_f32_e32 v219, v219, v217
	s_nop 1
	v_add_f32_dpp v216, v218, v218 row_ror:8 row_mask:0xf bank_mask:0xf
	v_add_f32_dpp v217, v219, v219 row_ror:8 row_mask:0xf bank_mask:0xf
	v_cndmask_b32_e64 v216, v216, v217, s[84:85]
	s_and_saveexec_b64 s[82:83], s[4:5]
	global_atomic_add_f32 v163, v216, s[12:13]
	s_or_b64 exec, exec, s[82:83]
	s_mov_b64 s[24:25], exec
	s_branch .LBB0_743
